# gate/up weight conversion moved out of phase 0 into the wait of grid seams 0,1,3 (waves 1-7 convert 2 tiles each while wave 0 runs the barrier); same bf16 RNE conversion
# speedup vs baseline: 1.0185x; 1.0185x over previous
_Z9block_fwd4Args:
	v_writelane_b32 v237, s0, 0
	v_writelane_b32 v237, s1, 1
	s_load_dwordx8 s[24:31], s[0:1], 0x80
	s_add_u32 s4, s0, 0x98
	s_addc_u32 s5, s1, 0
	v_and_b32_e32 v208, 0x3ff, v0
	s_mov_b32 s89, s2
	s_waitcnt lgkmcnt(0)
	s_and_b32 s3, s30, 7
	s_cmp_eq_u32 s3, 0
	v_readfirstlane_b32 s56, v208
	s_mov_b32 s33, 0
	s_cselect_b64 s[90:91], -1, 0
	s_cmp_lg_u32 s3, 0
	s_mov_b32 s3, s2
	s_cbranch_scc1 .LBB0_2
	s_ashr_i32 s6, s2, 31
	s_lshr_b32 s6, s6, 29
	s_add_i32 s6, s2, s6
	s_and_b32 s7, s6, -8
	s_ashr_i32 s3, s30, 3
	s_sub_i32 s7, s2, s7
	s_mul_i32 s3, s3, s7
	s_ashr_i32 s6, s6, 3
	s_add_i32 s3, s3, s6

.LBB0_21:
	s_lshr_b32 s95, s56, 6
	s_add_u32 s56, s26, 0x200000
	s_addc_u32 s57, s27, 0
	s_add_u32 s6, s26, 0x1a00000
	s_addc_u32 s7, s27, 0
	s_add_u32 s52, s26, 0x2200000
	s_addc_u32 s53, s27, 0
	s_add_u32 s58, s26, 0x100000
	s_addc_u32 s59, s27, 0
	s_cmp_lt_i32 s28, 1
	s_cselect_b64 s[0:1], -1, 0
	s_cmp_gt_i32 s29, 0
	s_cselect_b64 s[4:5], -1, 0
	s_and_b64 s[60:61], s[0:1], s[4:5]
	s_andn2_b64 vcc, exec, s[60:61]
	v_and_b32_e32 v209, 63, v208
	s_cbranch_vccnz .LBB0_253
	s_lshl_b32 s0, s3, 3
	s_add_i32 s62, s0, s95
	s_lshl_b32 s64, s30, 3
	s_cmpk_gt_i32 s62, 0x21ff
	s_cbranch_scc1 .LBB0_241
	s_lshl_b32 s0, s95, 14
	v_lshrrev_b32_e32 v76, 5, v209
	v_and_b32_e32 v12, 31, v208
	s_add_i32 s4, s0, 0
	v_lshlrev_b32_e32 v8, 2, v12
	v_mul_u32_u24_e32 v0, 0x84, v76
	s_waitcnt lgkmcnt(0)
	s_cmp_lg_u64 s[16:17], 0
	v_add3_u32 v77, s4, v8, v0
	v_lshlrev_b32_e32 v0, 3, v208
	v_mov_b32_e32 v1, 0
	s_cselect_b64 s[0:1], -1, 0
	v_lshrrev_b32_e32 v78, 3, v209
	v_and_b32_e32 v0, 56, v0
	s_cmp_lg_u64 s[10:11], 0
	v_mul_u32_u24_e32 v4, 0x84, v0
	v_lshlrev_b32_e32 v0, 1, v0
	v_lshlrev_b32_e32 v5, 2, v78
	v_mov_b32_e32 v9, v1
	s_cselect_b64 s[66:67], -1, 0
	s_cmp_lg_u64 s[38:39], 0
	s_mov_b32 s5, 0
	v_lshl_add_u64 v[2:3], s[52:53], 0, v[0:1]
	v_add3_u32 v79, s4, v4, v5
	v_or_b32_e32 v80, 8, v78
	v_or_b32_e32 v81, 16, v78
	v_or_b32_e32 v82, 24, v78
	v_lshl_add_u64 v[4:5], s[14:15], 0, v[8:9]
	v_lshl_add_u64 v[6:7], s[6:7], 0, v[0:1]
	v_lshl_add_u64 v[8:9], s[40:41], 0, v[8:9]
	s_cselect_b64 s[14:15], -1, 0
	v_lshl_add_u64 v[10:11], s[56:57], 0, v[0:1]
	s_lshl_b32 s63, s62, 5
	s_lshl_b32 s65, s64, 5
	s_lshl_b32 s74, s62, 7
	s_lshl_b32 s75, s64, 7
	s_movk_i32 s76, 0xca00
	v_lshlrev_b32_e32 v12, 2, v12
	s_movk_i32 s77, 0x5800
	s_movk_i32 s78, 0x7fff
	s_mov_b32 s79, 0xffff0000
	s_movk_i32 s80, 0x6000
	s_xor_b64 s[40:41], s[0:1], -1
	s_xor_b64 s[66:67], s[66:67], -1
	s_mov_b32 s81, s62
	s_branch .LBB0_26

.LBB0_25:
	s_add_i32 s81, s81, s64
	s_add_i32 s63, s63, s65
	s_add_i32 s74, s74, s75
	s_cmpk_gt_i32 s81, 0x21ff
	s_cbranch_scc1 .LBB0_241

.LBB0_253:
	s_cmp_gt_i32 s29, 1
	s_cselect_b64 s[0:1], -1, 0
	s_and_b64 s[4:5], s[60:61], s[0:1]
	s_andn2_b64 vcc, exec, s[4:5]
	s_cbranch_vccnz .LBB0_303
	s_waitcnt vmcnt(0)
	v_cmp_eq_u32_e32 vcc, 0, v208
	s_waitcnt lgkmcnt(0)
	s_barrier
	v_readfirstlane_b32 s3, v208
	s_nop 3
	s_lshr_b32 s3, s3, 6
	s_cmp_eq_u32 s3, 0
	s_cbranch_scc1 .Lmy_cv0_end
	v_readlane_b32 s36, v237, 0
	v_readlane_b32 s37, v237, 1
	s_mul_i32 s4, s2, 7
	s_add_i32 s4, s4, s3
	s_add_i32 s66, s4, 511
	s_lshl_b32 s72, s3, 14
	s_nop 4
	s_load_dwordx4 s[60:63], s[36:37], 0x60
	s_load_dwordx2 s[64:65], s[36:37], 0x70
	v_lshrrev_b32_e32 v6, 5, v209
	v_and_b32_e32 v7, 31, v209
	v_mul_u32_u24_e32 v0, 0x1600, v6
	v_add_lshl_u32 v0, v0, v7, 2
	v_mul_u32_u24_e32 v2, 33, v6
	v_add_lshl_u32 v2, v2, v7, 2
	v_add_u32_e32 v2, s72, v2
	v_and_b32_e32 v8, 7, v209
	v_lshrrev_b32_e32 v9, 3, v209
	v_mul_u32_u24_e32 v3, 0x108, v8
	v_add_lshl_u32 v3, v3, v9, 2
	v_add_u32_e32 v3, s72, v3
	v_lshlrev_b32_e32 v4, 12, v9
	v_lshl_add_u32 v4, v8, 4, v4
	v_lshlrev_b32_e32 v5, 5, v8
	s_waitcnt lgkmcnt(0)
	s_cmpk_ge_u32 s66, 0x1600
	s_cselect_b32 s68, s64, s62
	s_cselect_b32 s69, s65, s63
	s_cselect_b32 s54, 128, 0
	s_cselect_b32 s41, 0x1600, 0
	s_sub_u32 s41, s66, s41
	s_mul_hi_u32 s4, s41, 0xba2e8ba3
	s_lshr_b32 s4, s4, 7
	s_mul_i32 s70, s4, 0xb0
	s_sub_u32 s5, s41, s70
	s_mul_i32 s70, s4, 0x160000
	s_lshl_b32 s71, s5, 7
	s_add_u32 s68, s68, s70
	s_addc_u32 s69, s69, 0
	s_add_u32 s68, s68, s71
	s_addc_u32 s69, s69, 0
	v_mov_b32_e32 v1, v0
	global_load_dword v32, v1, s[68:69] nt
	v_add_u32_e32 v1, 0xb000, v1
	global_load_dword v33, v1, s[68:69] nt
	v_add_u32_e32 v1, 0xb000, v1
	global_load_dword v34, v1, s[68:69] nt
	v_add_u32_e32 v1, 0xb000, v1
	global_load_dword v35, v1, s[68:69] nt
	v_add_u32_e32 v1, 0xb000, v1
	global_load_dword v36, v1, s[68:69] nt
	v_add_u32_e32 v1, 0xb000, v1
	global_load_dword v37, v1, s[68:69] nt
	v_add_u32_e32 v1, 0xb000, v1
	global_load_dword v38, v1, s[68:69] nt
	v_add_u32_e32 v1, 0xb000, v1
	global_load_dword v39, v1, s[68:69] nt
	v_add_u32_e32 v1, 0xb000, v1
	global_load_dword v40, v1, s[68:69] nt
	v_add_u32_e32 v1, 0xb000, v1
	global_load_dword v41, v1, s[68:69] nt
	v_add_u32_e32 v1, 0xb000, v1
	global_load_dword v42, v1, s[68:69] nt
	v_add_u32_e32 v1, 0xb000, v1
	global_load_dword v43, v1, s[68:69] nt
	v_add_u32_e32 v1, 0xb000, v1
	global_load_dword v44, v1, s[68:69] nt
	v_add_u32_e32 v1, 0xb000, v1
	global_load_dword v45, v1, s[68:69] nt
	v_add_u32_e32 v1, 0xb000, v1
	global_load_dword v46, v1, s[68:69] nt
	v_add_u32_e32 v1, 0xb000, v1
	global_load_dword v47, v1, s[68:69] nt
	v_add_u32_e32 v1, 0xb000, v1
	global_load_dword v48, v1, s[68:69] nt
	v_add_u32_e32 v1, 0xb000, v1
	global_load_dword v49, v1, s[68:69] nt
	v_add_u32_e32 v1, 0xb000, v1
	global_load_dword v50, v1, s[68:69] nt
	v_add_u32_e32 v1, 0xb000, v1
	global_load_dword v51, v1, s[68:69] nt
	v_add_u32_e32 v1, 0xb000, v1
	global_load_dword v52, v1, s[68:69] nt
	v_add_u32_e32 v1, 0xb000, v1
	global_load_dword v53, v1, s[68:69] nt
	v_add_u32_e32 v1, 0xb000, v1
	global_load_dword v54, v1, s[68:69] nt
	v_add_u32_e32 v1, 0xb000, v1
	global_load_dword v55, v1, s[68:69] nt
	v_add_u32_e32 v1, 0xb000, v1
	global_load_dword v56, v1, s[68:69] nt
	v_add_u32_e32 v1, 0xb000, v1
	global_load_dword v57, v1, s[68:69] nt
	v_add_u32_e32 v1, 0xb000, v1
	global_load_dword v58, v1, s[68:69] nt
	v_add_u32_e32 v1, 0xb000, v1
	global_load_dword v59, v1, s[68:69] nt
	v_add_u32_e32 v1, 0xb000, v1
	global_load_dword v60, v1, s[68:69] nt
	v_add_u32_e32 v1, 0xb000, v1
	global_load_dword v61, v1, s[68:69] nt
	v_add_u32_e32 v1, 0xb000, v1
	global_load_dword v62, v1, s[68:69] nt
	v_add_u32_e32 v1, 0xb000, v1
	global_load_dword v63, v1, s[68:69] nt
	s_lshl_b32 s70, s4, 8
	s_add_u32 s70, s60, s70
	s_addc_u32 s71, s61, 0
	global_load_dwordx4 v[96:99], v5, s[70:71]
	global_load_dwordx4 v[100:103], v5, s[70:71] offset:16
	s_addk_i32 s66, 0x700
	s_cmpk_ge_u32 s66, 0x1600
	s_cselect_b32 s68, s64, s62
	s_cselect_b32 s69, s65, s63
	s_cselect_b32 s40, 128, 0
	s_cselect_b32 s41, 0x1600, 0
	s_sub_u32 s41, s66, s41
	s_mul_hi_u32 s55, s41, 0xba2e8ba3
	s_lshr_b32 s55, s55, 7
	s_mul_i32 s70, s55, 0xb0
	s_sub_u32 s67, s41, s70
	s_mul_i32 s70, s55, 0x160000
	s_lshl_b32 s71, s67, 7
	s_add_u32 s68, s68, s70
	s_addc_u32 s69, s69, 0
	s_add_u32 s68, s68, s71
	s_addc_u32 s69, s69, 0
	v_mov_b32_e32 v1, v0
	global_load_dword v64, v1, s[68:69] nt
	v_add_u32_e32 v1, 0xb000, v1
	global_load_dword v65, v1, s[68:69] nt
	v_add_u32_e32 v1, 0xb000, v1
	global_load_dword v66, v1, s[68:69] nt
	v_add_u32_e32 v1, 0xb000, v1
	global_load_dword v67, v1, s[68:69] nt
	v_add_u32_e32 v1, 0xb000, v1
	global_load_dword v68, v1, s[68:69] nt
	v_add_u32_e32 v1, 0xb000, v1
	global_load_dword v69, v1, s[68:69] nt
	v_add_u32_e32 v1, 0xb000, v1
	global_load_dword v70, v1, s[68:69] nt
	v_add_u32_e32 v1, 0xb000, v1
	global_load_dword v71, v1, s[68:69] nt
	v_add_u32_e32 v1, 0xb000, v1
	global_load_dword v72, v1, s[68:69] nt
	v_add_u32_e32 v1, 0xb000, v1
	global_load_dword v73, v1, s[68:69] nt
	v_add_u32_e32 v1, 0xb000, v1
	global_load_dword v74, v1, s[68:69] nt
	v_add_u32_e32 v1, 0xb000, v1
	global_load_dword v75, v1, s[68:69] nt
	v_add_u32_e32 v1, 0xb000, v1
	global_load_dword v76, v1, s[68:69] nt
	v_add_u32_e32 v1, 0xb000, v1
	global_load_dword v77, v1, s[68:69] nt
	v_add_u32_e32 v1, 0xb000, v1
	global_load_dword v78, v1, s[68:69] nt
	v_add_u32_e32 v1, 0xb000, v1
	global_load_dword v79, v1, s[68:69] nt
	v_add_u32_e32 v1, 0xb000, v1
	global_load_dword v80, v1, s[68:69] nt
	v_add_u32_e32 v1, 0xb000, v1
	global_load_dword v81, v1, s[68:69] nt
	v_add_u32_e32 v1, 0xb000, v1
	global_load_dword v82, v1, s[68:69] nt
	v_add_u32_e32 v1, 0xb000, v1
	global_load_dword v83, v1, s[68:69] nt
	v_add_u32_e32 v1, 0xb000, v1
	global_load_dword v84, v1, s[68:69] nt
	v_add_u32_e32 v1, 0xb000, v1
	global_load_dword v85, v1, s[68:69] nt
	v_add_u32_e32 v1, 0xb000, v1
	global_load_dword v86, v1, s[68:69] nt
	v_add_u32_e32 v1, 0xb000, v1
	global_load_dword v87, v1, s[68:69] nt
	v_add_u32_e32 v1, 0xb000, v1
	global_load_dword v88, v1, s[68:69] nt
	v_add_u32_e32 v1, 0xb000, v1
	global_load_dword v89, v1, s[68:69] nt
	v_add_u32_e32 v1, 0xb000, v1
	global_load_dword v90, v1, s[68:69] nt
	v_add_u32_e32 v1, 0xb000, v1
	global_load_dword v91, v1, s[68:69] nt
	v_add_u32_e32 v1, 0xb000, v1
	global_load_dword v92, v1, s[68:69] nt
	v_add_u32_e32 v1, 0xb000, v1
	global_load_dword v93, v1, s[68:69] nt
	v_add_u32_e32 v1, 0xb000, v1
	global_load_dword v94, v1, s[68:69] nt
	v_add_u32_e32 v1, 0xb000, v1
	global_load_dword v95, v1, s[68:69] nt
	s_lshl_b32 s70, s55, 8
	s_add_u32 s70, s60, s70
	s_addc_u32 s71, s61, 0
	global_load_dwordx4 v[104:107], v5, s[70:71]
	global_load_dwordx4 v[108:111], v5, s[70:71] offset:16
	s_waitcnt vmcnt(34)
	ds_write_b32 v2, v32 offset:0
	ds_write_b32 v2, v33 offset:264
	ds_write_b32 v2, v34 offset:528
	ds_write_b32 v2, v35 offset:792
	ds_write_b32 v2, v36 offset:1056
	ds_write_b32 v2, v37 offset:1320
	ds_write_b32 v2, v38 offset:1584
	ds_write_b32 v2, v39 offset:1848
	ds_write_b32 v2, v40 offset:2112
	ds_write_b32 v2, v41 offset:2376
	ds_write_b32 v2, v42 offset:2640
	ds_write_b32 v2, v43 offset:2904
	ds_write_b32 v2, v44 offset:3168
	ds_write_b32 v2, v45 offset:3432
	ds_write_b32 v2, v46 offset:3696
	ds_write_b32 v2, v47 offset:3960
	ds_write_b32 v2, v48 offset:4224
	ds_write_b32 v2, v49 offset:4488
	ds_write_b32 v2, v50 offset:4752
	ds_write_b32 v2, v51 offset:5016
	ds_write_b32 v2, v52 offset:5280
	ds_write_b32 v2, v53 offset:5544
	ds_write_b32 v2, v54 offset:5808
	ds_write_b32 v2, v55 offset:6072
	ds_write_b32 v2, v56 offset:6336
	ds_write_b32 v2, v57 offset:6600
	ds_write_b32 v2, v58 offset:6864
	ds_write_b32 v2, v59 offset:7128
	ds_write_b32 v2, v60 offset:7392
	ds_write_b32 v2, v61 offset:7656
	ds_write_b32 v2, v62 offset:7920
	ds_write_b32 v2, v63 offset:8184
	s_lshr_b32 s70, s5, 2
	s_lshl_b32 s70, s70, 8
	s_and_b32 s71, s5, 3
	s_lshl_b32 s71, s71, 5
	s_add_i32 s70, s70, s71
	s_add_i32 s70, s70, s54
	s_lshl_b32 s70, s70, 12
	s_lshl_b32 s71, s4, 7
	s_add_i32 s70, s70, s71
	s_add_u32 s70, s70, 0x2200000
	s_add_u32 s70, s26, s70
	s_addc_u32 s71, s27, 0
	s_waitcnt lgkmcnt(0)
	ds_read_b32 v10, v3 offset:0
	ds_read_b32 v11, v3 offset:132
	ds_read_b32 v12, v3 offset:264
	ds_read_b32 v13, v3 offset:396
	ds_read_b32 v14, v3 offset:528
	ds_read_b32 v15, v3 offset:660
	ds_read_b32 v16, v3 offset:792
	ds_read_b32 v17, v3 offset:924
	s_waitcnt lgkmcnt(0)
	v_mul_f32_e32 v10, v10, v96
	v_mul_f32_e32 v11, v11, v97
	v_mul_f32_e32 v12, v12, v98
	v_mul_f32_e32 v13, v13, v99
	v_mul_f32_e32 v14, v14, v100
	v_mul_f32_e32 v15, v15, v101
	v_mul_f32_e32 v16, v16, v102
	v_mul_f32_e32 v17, v17, v103
	v_cvt_pk_bf16_f32 v26, v10, v11
	v_cvt_pk_bf16_f32 v27, v12, v13
	v_cvt_pk_bf16_f32 v28, v14, v15
	v_cvt_pk_bf16_f32 v29, v16, v17
	v_mov_b32_e32 v9, v4
	global_store_dwordx4 v9, v[26:29], s[70:71]
	s_nop 1
	ds_read_b32 v10, v3 offset:32
	ds_read_b32 v11, v3 offset:164
	ds_read_b32 v12, v3 offset:296
	ds_read_b32 v13, v3 offset:428
	ds_read_b32 v14, v3 offset:560
	ds_read_b32 v15, v3 offset:692
	ds_read_b32 v16, v3 offset:824
	ds_read_b32 v17, v3 offset:956
	s_waitcnt lgkmcnt(0)
	v_mul_f32_e32 v10, v10, v96
	v_mul_f32_e32 v11, v11, v97
	v_mul_f32_e32 v12, v12, v98
	v_mul_f32_e32 v13, v13, v99
	v_mul_f32_e32 v14, v14, v100
	v_mul_f32_e32 v15, v15, v101
	v_mul_f32_e32 v16, v16, v102
	v_mul_f32_e32 v17, v17, v103
	v_cvt_pk_bf16_f32 v26, v10, v11
	v_cvt_pk_bf16_f32 v27, v12, v13
	v_cvt_pk_bf16_f32 v28, v14, v15
	v_cvt_pk_bf16_f32 v29, v16, v17
	v_add_u32_e32 v9, 0x8000, v9
	global_store_dwordx4 v9, v[26:29], s[70:71]
	s_nop 1
	ds_read_b32 v10, v3 offset:64
	ds_read_b32 v11, v3 offset:196
	ds_read_b32 v12, v3 offset:328
	ds_read_b32 v13, v3 offset:460
	ds_read_b32 v14, v3 offset:592
	ds_read_b32 v15, v3 offset:724
	ds_read_b32 v16, v3 offset:856
	ds_read_b32 v17, v3 offset:988
	s_waitcnt lgkmcnt(0)
	v_mul_f32_e32 v10, v10, v96
	v_mul_f32_e32 v11, v11, v97
	v_mul_f32_e32 v12, v12, v98
	v_mul_f32_e32 v13, v13, v99
	v_mul_f32_e32 v14, v14, v100
	v_mul_f32_e32 v15, v15, v101
	v_mul_f32_e32 v16, v16, v102
	v_mul_f32_e32 v17, v17, v103
	v_cvt_pk_bf16_f32 v26, v10, v11
	v_cvt_pk_bf16_f32 v27, v12, v13
	v_cvt_pk_bf16_f32 v28, v14, v15
	v_cvt_pk_bf16_f32 v29, v16, v17
	v_add_u32_e32 v9, 0x8000, v9
	global_store_dwordx4 v9, v[26:29], s[70:71]
	s_nop 1
	ds_read_b32 v10, v3 offset:96
	ds_read_b32 v11, v3 offset:228
	ds_read_b32 v12, v3 offset:360
	ds_read_b32 v13, v3 offset:492
	ds_read_b32 v14, v3 offset:624
	ds_read_b32 v15, v3 offset:756
	ds_read_b32 v16, v3 offset:888
	ds_read_b32 v17, v3 offset:1020
	s_waitcnt lgkmcnt(0)
	v_mul_f32_e32 v10, v10, v96
	v_mul_f32_e32 v11, v11, v97
	v_mul_f32_e32 v12, v12, v98
	v_mul_f32_e32 v13, v13, v99
	v_mul_f32_e32 v14, v14, v100
	v_mul_f32_e32 v15, v15, v101
	v_mul_f32_e32 v16, v16, v102
	v_mul_f32_e32 v17, v17, v103
	v_cvt_pk_bf16_f32 v26, v10, v11
	v_cvt_pk_bf16_f32 v27, v12, v13
	v_cvt_pk_bf16_f32 v28, v14, v15
	v_cvt_pk_bf16_f32 v29, v16, v17
	v_add_u32_e32 v9, 0x8000, v9
	global_store_dwordx4 v9, v[26:29], s[70:71]
	s_nop 1
	s_waitcnt vmcnt(0)
	s_waitcnt lgkmcnt(0)
	ds_write_b32 v2, v64 offset:0
	ds_write_b32 v2, v65 offset:264
	ds_write_b32 v2, v66 offset:528
	ds_write_b32 v2, v67 offset:792
	ds_write_b32 v2, v68 offset:1056
	ds_write_b32 v2, v69 offset:1320
	ds_write_b32 v2, v70 offset:1584
	ds_write_b32 v2, v71 offset:1848
	ds_write_b32 v2, v72 offset:2112
	ds_write_b32 v2, v73 offset:2376
	ds_write_b32 v2, v74 offset:2640
	ds_write_b32 v2, v75 offset:2904
	ds_write_b32 v2, v76 offset:3168
	ds_write_b32 v2, v77 offset:3432
	ds_write_b32 v2, v78 offset:3696
	ds_write_b32 v2, v79 offset:3960
	ds_write_b32 v2, v80 offset:4224
	ds_write_b32 v2, v81 offset:4488
	ds_write_b32 v2, v82 offset:4752
	ds_write_b32 v2, v83 offset:5016
	ds_write_b32 v2, v84 offset:5280
	ds_write_b32 v2, v85 offset:5544
	ds_write_b32 v2, v86 offset:5808
	ds_write_b32 v2, v87 offset:6072
	ds_write_b32 v2, v88 offset:6336
	ds_write_b32 v2, v89 offset:6600
	ds_write_b32 v2, v90 offset:6864
	ds_write_b32 v2, v91 offset:7128
	ds_write_b32 v2, v92 offset:7392
	ds_write_b32 v2, v93 offset:7656
	ds_write_b32 v2, v94 offset:7920
	ds_write_b32 v2, v95 offset:8184
	s_lshr_b32 s70, s67, 2
	s_lshl_b32 s70, s70, 8
	s_and_b32 s71, s67, 3
	s_lshl_b32 s71, s71, 5
	s_add_i32 s70, s70, s71
	s_add_i32 s70, s70, s40
	s_lshl_b32 s70, s70, 12
	s_lshl_b32 s71, s55, 7
	s_add_i32 s70, s70, s71
	s_add_u32 s70, s70, 0x2200000
	s_add_u32 s70, s26, s70
	s_addc_u32 s71, s27, 0
	s_waitcnt lgkmcnt(0)
	ds_read_b32 v10, v3 offset:0
	ds_read_b32 v11, v3 offset:132
	ds_read_b32 v12, v3 offset:264
	ds_read_b32 v13, v3 offset:396
	ds_read_b32 v14, v3 offset:528
	ds_read_b32 v15, v3 offset:660
	ds_read_b32 v16, v3 offset:792
	ds_read_b32 v17, v3 offset:924
	s_waitcnt lgkmcnt(0)
	v_mul_f32_e32 v10, v10, v104
	v_mul_f32_e32 v11, v11, v105
	v_mul_f32_e32 v12, v12, v106
	v_mul_f32_e32 v13, v13, v107
	v_mul_f32_e32 v14, v14, v108
	v_mul_f32_e32 v15, v15, v109
	v_mul_f32_e32 v16, v16, v110
	v_mul_f32_e32 v17, v17, v111
	v_cvt_pk_bf16_f32 v26, v10, v11
	v_cvt_pk_bf16_f32 v27, v12, v13
	v_cvt_pk_bf16_f32 v28, v14, v15
	v_cvt_pk_bf16_f32 v29, v16, v17
	v_mov_b32_e32 v9, v4
	global_store_dwordx4 v9, v[26:29], s[70:71]
	s_nop 1
	ds_read_b32 v10, v3 offset:32
	ds_read_b32 v11, v3 offset:164
	ds_read_b32 v12, v3 offset:296
	ds_read_b32 v13, v3 offset:428
	ds_read_b32 v14, v3 offset:560
	ds_read_b32 v15, v3 offset:692
	ds_read_b32 v16, v3 offset:824
	ds_read_b32 v17, v3 offset:956
	s_waitcnt lgkmcnt(0)
	v_mul_f32_e32 v10, v10, v104
	v_mul_f32_e32 v11, v11, v105
	v_mul_f32_e32 v12, v12, v106
	v_mul_f32_e32 v13, v13, v107
	v_mul_f32_e32 v14, v14, v108
	v_mul_f32_e32 v15, v15, v109
	v_mul_f32_e32 v16, v16, v110
	v_mul_f32_e32 v17, v17, v111
	v_cvt_pk_bf16_f32 v26, v10, v11
	v_cvt_pk_bf16_f32 v27, v12, v13
	v_cvt_pk_bf16_f32 v28, v14, v15
	v_cvt_pk_bf16_f32 v29, v16, v17
	v_add_u32_e32 v9, 0x8000, v9
	global_store_dwordx4 v9, v[26:29], s[70:71]
	s_nop 1
	ds_read_b32 v10, v3 offset:64
	ds_read_b32 v11, v3 offset:196
	ds_read_b32 v12, v3 offset:328
	ds_read_b32 v13, v3 offset:460
	ds_read_b32 v14, v3 offset:592
	ds_read_b32 v15, v3 offset:724
	ds_read_b32 v16, v3 offset:856
	ds_read_b32 v17, v3 offset:988
	s_waitcnt lgkmcnt(0)
	v_mul_f32_e32 v10, v10, v104
	v_mul_f32_e32 v11, v11, v105
	v_mul_f32_e32 v12, v12, v106
	v_mul_f32_e32 v13, v13, v107
	v_mul_f32_e32 v14, v14, v108
	v_mul_f32_e32 v15, v15, v109
	v_mul_f32_e32 v16, v16, v110
	v_mul_f32_e32 v17, v17, v111
	v_cvt_pk_bf16_f32 v26, v10, v11
	v_cvt_pk_bf16_f32 v27, v12, v13
	v_cvt_pk_bf16_f32 v28, v14, v15
	v_cvt_pk_bf16_f32 v29, v16, v17
	v_add_u32_e32 v9, 0x8000, v9
	global_store_dwordx4 v9, v[26:29], s[70:71]
	s_nop 1
	ds_read_b32 v10, v3 offset:96
	ds_read_b32 v11, v3 offset:228
	ds_read_b32 v12, v3 offset:360
	ds_read_b32 v13, v3 offset:492
	ds_read_b32 v14, v3 offset:624
	ds_read_b32 v15, v3 offset:756
	ds_read_b32 v16, v3 offset:888
	ds_read_b32 v17, v3 offset:1020
	s_waitcnt lgkmcnt(0)
	v_mul_f32_e32 v10, v10, v104
	v_mul_f32_e32 v11, v11, v105
	v_mul_f32_e32 v12, v12, v106
	v_mul_f32_e32 v13, v13, v107
	v_mul_f32_e32 v14, v14, v108
	v_mul_f32_e32 v15, v15, v109
	v_mul_f32_e32 v16, v16, v110
	v_mul_f32_e32 v17, v17, v111
	v_cvt_pk_bf16_f32 v26, v10, v11
	v_cvt_pk_bf16_f32 v27, v12, v13
	v_cvt_pk_bf16_f32 v28, v14, v15
	v_cvt_pk_bf16_f32 v29, v16, v17
	v_add_u32_e32 v9, 0x8000, v9
	global_store_dwordx4 v9, v[26:29], s[70:71]
	s_nop 1
	s_waitcnt vmcnt(0) lgkmcnt(0)
.Lmy_cv0_end:
	v_cmp_eq_u32_e32 vcc, 0, v208
	s_nop 3
	s_and_saveexec_b64 s[4:5], vcc
	s_cbranch_execz .LBB0_302
	v_mov_b32_e32 v0, s88
	s_waitcnt vmcnt(0) expcnt(0) lgkmcnt(0)
	ds_read_b32 v2, v0
	ds_read_b32 v0, v0 offset:4
	s_waitcnt lgkmcnt(1)
	v_cmp_ne_u32_e32 vcc, 0, v2
	s_cbranch_vccnz .LBB0_270
	s_add_u32 s10, s26, 0xfc00200
	s_addc_u32 s11, s27, 0
	s_add_u32 s14, s26, 0xfc00400
	s_addc_u32 s15, s27, 0
	s_add_u32 s16, s26, 0xfc00500
	s_addc_u32 s17, s27, 0
	s_add_u32 s18, s26, 0xfc00600
	s_addc_u32 s19, s27, 0
	s_add_u32 s20, s26, 0xfc00700
	s_addc_u32 s21, s27, 0
	s_add_u32 s36, s26, 0xfc00800
	s_addc_u32 s37, s27, 0
	s_add_u32 s38, s26, 0xfc00900
	s_addc_u32 s39, s27, 0
	s_add_u32 s40, s26, 0xfc00a00
	s_addc_u32 s41, s27, 0
	s_add_u32 s60, s26, 0xfc00b00
	s_addc_u32 s61, s27, 0
	s_add_u32 s62, s26, 0xfc00c00
	s_addc_u32 s63, s27, 0
	s_add_u32 s64, s26, 0xfc00d00
	s_addc_u32 s65, s27, 0
	s_add_u32 s66, s26, 0xfc00e00
	s_addc_u32 s67, s27, 0
	s_add_u32 s68, s26, 0xfc00f00
	s_addc_u32 s69, s27, 0
	s_add_u32 s70, s26, 0xfc01000
	s_addc_u32 s71, s27, 0
	s_add_u32 s72, s26, 0xfc01100
	s_addc_u32 s73, s27, 0
	s_add_u32 s74, s26, 0xfc01200
	s_addc_u32 s75, s27, 0
	s_mul_i32 s3, s31, s94
	s_add_u32 s76, s26, 0xfc01300
	s_mul_i32 s3, s3, s30
	s_addc_u32 s77, s27, 0
	s_mov_b32 s84, 1
	v_mov_b32_e32 v16, 0
	s_branch .LBB0_258

.LBB0_340:
	s_cmp_gt_u32 s29, 2
	s_cselect_b64 s[0:1], -1, 0
	s_and_b64 s[0:1], s[20:21], s[0:1]
	s_andn2_b64 vcc, exec, s[0:1]
	s_cbranch_vccnz .LBB0_392
	s_waitcnt vmcnt(0)
	v_cmp_eq_u32_e32 vcc, 0, v208
	s_waitcnt vmcnt(0) lgkmcnt(0)
	s_barrier
	v_readfirstlane_b32 s3, v208
	s_nop 3
	s_lshr_b32 s3, s3, 6
	s_cmp_eq_u32 s3, 0
	s_cbranch_scc1 .Lmy_cv1_end
	v_readlane_b32 s36, v237, 0
	v_readlane_b32 s37, v237, 1
	s_mul_i32 s4, s2, 7
	s_add_i32 s4, s4, s3
	s_add_i32 s66, s4, 4095
	s_lshl_b32 s72, s3, 14
	s_nop 4
	s_load_dwordx4 s[60:63], s[36:37], 0x60
	s_load_dwordx2 s[64:65], s[36:37], 0x70
	v_lshrrev_b32_e32 v6, 5, v209
	v_and_b32_e32 v7, 31, v209
	v_mul_u32_u24_e32 v0, 0x1600, v6
	v_add_lshl_u32 v0, v0, v7, 2
	v_mul_u32_u24_e32 v2, 33, v6
	v_add_lshl_u32 v2, v2, v7, 2
	v_add_u32_e32 v2, s72, v2
	v_and_b32_e32 v8, 7, v209
	v_lshrrev_b32_e32 v9, 3, v209
	v_mul_u32_u24_e32 v3, 0x108, v8
	v_add_lshl_u32 v3, v3, v9, 2
	v_add_u32_e32 v3, s72, v3
	v_lshlrev_b32_e32 v4, 12, v9
	v_lshl_add_u32 v4, v8, 4, v4
	v_lshlrev_b32_e32 v5, 5, v8
	s_waitcnt lgkmcnt(0)
	s_cmpk_ge_u32 s66, 0x1600
	s_cselect_b32 s68, s64, s62
	s_cselect_b32 s69, s65, s63
	s_cselect_b32 s54, 128, 0
	s_cselect_b32 s41, 0x1600, 0
	s_sub_u32 s41, s66, s41
	s_mul_hi_u32 s4, s41, 0xba2e8ba3
	s_lshr_b32 s4, s4, 7
	s_mul_i32 s70, s4, 0xb0
	s_sub_u32 s5, s41, s70
	s_mul_i32 s70, s4, 0x160000
	s_lshl_b32 s71, s5, 7
	s_add_u32 s68, s68, s70
	s_addc_u32 s69, s69, 0
	s_add_u32 s68, s68, s71
	s_addc_u32 s69, s69, 0
	v_mov_b32_e32 v1, v0
	global_load_dword v32, v1, s[68:69] nt
	v_add_u32_e32 v1, 0xb000, v1
	global_load_dword v33, v1, s[68:69] nt
	v_add_u32_e32 v1, 0xb000, v1
	global_load_dword v34, v1, s[68:69] nt
	v_add_u32_e32 v1, 0xb000, v1
	global_load_dword v35, v1, s[68:69] nt
	v_add_u32_e32 v1, 0xb000, v1
	global_load_dword v36, v1, s[68:69] nt
	v_add_u32_e32 v1, 0xb000, v1
	global_load_dword v37, v1, s[68:69] nt
	v_add_u32_e32 v1, 0xb000, v1
	global_load_dword v38, v1, s[68:69] nt
	v_add_u32_e32 v1, 0xb000, v1
	global_load_dword v39, v1, s[68:69] nt
	v_add_u32_e32 v1, 0xb000, v1
	global_load_dword v40, v1, s[68:69] nt
	v_add_u32_e32 v1, 0xb000, v1
	global_load_dword v41, v1, s[68:69] nt
	v_add_u32_e32 v1, 0xb000, v1
	global_load_dword v42, v1, s[68:69] nt
	v_add_u32_e32 v1, 0xb000, v1
	global_load_dword v43, v1, s[68:69] nt
	v_add_u32_e32 v1, 0xb000, v1
	global_load_dword v44, v1, s[68:69] nt
	v_add_u32_e32 v1, 0xb000, v1
	global_load_dword v45, v1, s[68:69] nt
	v_add_u32_e32 v1, 0xb000, v1
	global_load_dword v46, v1, s[68:69] nt
	v_add_u32_e32 v1, 0xb000, v1
	global_load_dword v47, v1, s[68:69] nt
	v_add_u32_e32 v1, 0xb000, v1
	global_load_dword v48, v1, s[68:69] nt
	v_add_u32_e32 v1, 0xb000, v1
	global_load_dword v49, v1, s[68:69] nt
	v_add_u32_e32 v1, 0xb000, v1
	global_load_dword v50, v1, s[68:69] nt
	v_add_u32_e32 v1, 0xb000, v1
	global_load_dword v51, v1, s[68:69] nt
	v_add_u32_e32 v1, 0xb000, v1
	global_load_dword v52, v1, s[68:69] nt
	v_add_u32_e32 v1, 0xb000, v1
	global_load_dword v53, v1, s[68:69] nt
	v_add_u32_e32 v1, 0xb000, v1
	global_load_dword v54, v1, s[68:69] nt
	v_add_u32_e32 v1, 0xb000, v1
	global_load_dword v55, v1, s[68:69] nt
	v_add_u32_e32 v1, 0xb000, v1
	global_load_dword v56, v1, s[68:69] nt
	v_add_u32_e32 v1, 0xb000, v1
	global_load_dword v57, v1, s[68:69] nt
	v_add_u32_e32 v1, 0xb000, v1
	global_load_dword v58, v1, s[68:69] nt
	v_add_u32_e32 v1, 0xb000, v1
	global_load_dword v59, v1, s[68:69] nt
	v_add_u32_e32 v1, 0xb000, v1
	global_load_dword v60, v1, s[68:69] nt
	v_add_u32_e32 v1, 0xb000, v1
	global_load_dword v61, v1, s[68:69] nt
	v_add_u32_e32 v1, 0xb000, v1
	global_load_dword v62, v1, s[68:69] nt
	v_add_u32_e32 v1, 0xb000, v1
	global_load_dword v63, v1, s[68:69] nt
	s_lshl_b32 s70, s4, 8
	s_add_u32 s70, s60, s70
	s_addc_u32 s71, s61, 0
	global_load_dwordx4 v[96:99], v5, s[70:71]
	global_load_dwordx4 v[100:103], v5, s[70:71] offset:16
	s_addk_i32 s66, 0x700
	s_cmpk_ge_u32 s66, 0x1600
	s_cselect_b32 s68, s64, s62
	s_cselect_b32 s69, s65, s63
	s_cselect_b32 s40, 128, 0
	s_cselect_b32 s41, 0x1600, 0
	s_sub_u32 s41, s66, s41
	s_mul_hi_u32 s55, s41, 0xba2e8ba3
	s_lshr_b32 s55, s55, 7
	s_mul_i32 s70, s55, 0xb0
	s_sub_u32 s67, s41, s70
	s_mul_i32 s70, s55, 0x160000
	s_lshl_b32 s71, s67, 7
	s_add_u32 s68, s68, s70
	s_addc_u32 s69, s69, 0
	s_add_u32 s68, s68, s71
	s_addc_u32 s69, s69, 0
	v_mov_b32_e32 v1, v0
	global_load_dword v64, v1, s[68:69] nt
	v_add_u32_e32 v1, 0xb000, v1
	global_load_dword v65, v1, s[68:69] nt
	v_add_u32_e32 v1, 0xb000, v1
	global_load_dword v66, v1, s[68:69] nt
	v_add_u32_e32 v1, 0xb000, v1
	global_load_dword v67, v1, s[68:69] nt
	v_add_u32_e32 v1, 0xb000, v1
	global_load_dword v68, v1, s[68:69] nt
	v_add_u32_e32 v1, 0xb000, v1
	global_load_dword v69, v1, s[68:69] nt
	v_add_u32_e32 v1, 0xb000, v1
	global_load_dword v70, v1, s[68:69] nt
	v_add_u32_e32 v1, 0xb000, v1
	global_load_dword v71, v1, s[68:69] nt
	v_add_u32_e32 v1, 0xb000, v1
	global_load_dword v72, v1, s[68:69] nt
	v_add_u32_e32 v1, 0xb000, v1
	global_load_dword v73, v1, s[68:69] nt
	v_add_u32_e32 v1, 0xb000, v1
	global_load_dword v74, v1, s[68:69] nt
	v_add_u32_e32 v1, 0xb000, v1
	global_load_dword v75, v1, s[68:69] nt
	v_add_u32_e32 v1, 0xb000, v1
	global_load_dword v76, v1, s[68:69] nt
	v_add_u32_e32 v1, 0xb000, v1
	global_load_dword v77, v1, s[68:69] nt
	v_add_u32_e32 v1, 0xb000, v1
	global_load_dword v78, v1, s[68:69] nt
	v_add_u32_e32 v1, 0xb000, v1
	global_load_dword v79, v1, s[68:69] nt
	v_add_u32_e32 v1, 0xb000, v1
	global_load_dword v80, v1, s[68:69] nt
	v_add_u32_e32 v1, 0xb000, v1
	global_load_dword v81, v1, s[68:69] nt
	v_add_u32_e32 v1, 0xb000, v1
	global_load_dword v82, v1, s[68:69] nt
	v_add_u32_e32 v1, 0xb000, v1
	global_load_dword v83, v1, s[68:69] nt
	v_add_u32_e32 v1, 0xb000, v1
	global_load_dword v84, v1, s[68:69] nt
	v_add_u32_e32 v1, 0xb000, v1
	global_load_dword v85, v1, s[68:69] nt
	v_add_u32_e32 v1, 0xb000, v1
	global_load_dword v86, v1, s[68:69] nt
	v_add_u32_e32 v1, 0xb000, v1
	global_load_dword v87, v1, s[68:69] nt
	v_add_u32_e32 v1, 0xb000, v1
	global_load_dword v88, v1, s[68:69] nt
	v_add_u32_e32 v1, 0xb000, v1
	global_load_dword v89, v1, s[68:69] nt
	v_add_u32_e32 v1, 0xb000, v1
	global_load_dword v90, v1, s[68:69] nt
	v_add_u32_e32 v1, 0xb000, v1
	global_load_dword v91, v1, s[68:69] nt
	v_add_u32_e32 v1, 0xb000, v1
	global_load_dword v92, v1, s[68:69] nt
	v_add_u32_e32 v1, 0xb000, v1
	global_load_dword v93, v1, s[68:69] nt
	v_add_u32_e32 v1, 0xb000, v1
	global_load_dword v94, v1, s[68:69] nt
	v_add_u32_e32 v1, 0xb000, v1
	global_load_dword v95, v1, s[68:69] nt
	s_lshl_b32 s70, s55, 8
	s_add_u32 s70, s60, s70
	s_addc_u32 s71, s61, 0
	global_load_dwordx4 v[104:107], v5, s[70:71]
	global_load_dwordx4 v[108:111], v5, s[70:71] offset:16
	s_waitcnt vmcnt(34)
	ds_write_b32 v2, v32 offset:0
	ds_write_b32 v2, v33 offset:264
	ds_write_b32 v2, v34 offset:528
	ds_write_b32 v2, v35 offset:792
	ds_write_b32 v2, v36 offset:1056
	ds_write_b32 v2, v37 offset:1320
	ds_write_b32 v2, v38 offset:1584
	ds_write_b32 v2, v39 offset:1848
	ds_write_b32 v2, v40 offset:2112
	ds_write_b32 v2, v41 offset:2376
	ds_write_b32 v2, v42 offset:2640
	ds_write_b32 v2, v43 offset:2904
	ds_write_b32 v2, v44 offset:3168
	ds_write_b32 v2, v45 offset:3432
	ds_write_b32 v2, v46 offset:3696
	ds_write_b32 v2, v47 offset:3960
	ds_write_b32 v2, v48 offset:4224
	ds_write_b32 v2, v49 offset:4488
	ds_write_b32 v2, v50 offset:4752
	ds_write_b32 v2, v51 offset:5016
	ds_write_b32 v2, v52 offset:5280
	ds_write_b32 v2, v53 offset:5544
	ds_write_b32 v2, v54 offset:5808
	ds_write_b32 v2, v55 offset:6072
	ds_write_b32 v2, v56 offset:6336
	ds_write_b32 v2, v57 offset:6600
	ds_write_b32 v2, v58 offset:6864
	ds_write_b32 v2, v59 offset:7128
	ds_write_b32 v2, v60 offset:7392
	ds_write_b32 v2, v61 offset:7656
	ds_write_b32 v2, v62 offset:7920
	ds_write_b32 v2, v63 offset:8184
	s_lshr_b32 s70, s5, 2
	s_lshl_b32 s70, s70, 8
	s_and_b32 s71, s5, 3
	s_lshl_b32 s71, s71, 5
	s_add_i32 s70, s70, s71
	s_add_i32 s70, s70, s54
	s_lshl_b32 s70, s70, 12
	s_lshl_b32 s71, s4, 7
	s_add_i32 s70, s70, s71
	s_add_u32 s70, s70, 0x2200000
	s_add_u32 s70, s26, s70
	s_addc_u32 s71, s27, 0
	s_waitcnt lgkmcnt(0)
	ds_read_b32 v10, v3 offset:0
	ds_read_b32 v11, v3 offset:132
	ds_read_b32 v12, v3 offset:264
	ds_read_b32 v13, v3 offset:396
	ds_read_b32 v14, v3 offset:528
	ds_read_b32 v15, v3 offset:660
	ds_read_b32 v16, v3 offset:792
	ds_read_b32 v17, v3 offset:924
	s_waitcnt lgkmcnt(0)
	v_mul_f32_e32 v10, v10, v96
	v_mul_f32_e32 v11, v11, v97
	v_mul_f32_e32 v12, v12, v98
	v_mul_f32_e32 v13, v13, v99
	v_mul_f32_e32 v14, v14, v100
	v_mul_f32_e32 v15, v15, v101
	v_mul_f32_e32 v16, v16, v102
	v_mul_f32_e32 v17, v17, v103
	v_cvt_pk_bf16_f32 v26, v10, v11
	v_cvt_pk_bf16_f32 v27, v12, v13
	v_cvt_pk_bf16_f32 v28, v14, v15
	v_cvt_pk_bf16_f32 v29, v16, v17
	v_mov_b32_e32 v9, v4
	global_store_dwordx4 v9, v[26:29], s[70:71]
	s_nop 1
	ds_read_b32 v10, v3 offset:32
	ds_read_b32 v11, v3 offset:164
	ds_read_b32 v12, v3 offset:296
	ds_read_b32 v13, v3 offset:428
	ds_read_b32 v14, v3 offset:560
	ds_read_b32 v15, v3 offset:692
	ds_read_b32 v16, v3 offset:824
	ds_read_b32 v17, v3 offset:956
	s_waitcnt lgkmcnt(0)
	v_mul_f32_e32 v10, v10, v96
	v_mul_f32_e32 v11, v11, v97
	v_mul_f32_e32 v12, v12, v98
	v_mul_f32_e32 v13, v13, v99
	v_mul_f32_e32 v14, v14, v100
	v_mul_f32_e32 v15, v15, v101
	v_mul_f32_e32 v16, v16, v102
	v_mul_f32_e32 v17, v17, v103
	v_cvt_pk_bf16_f32 v26, v10, v11
	v_cvt_pk_bf16_f32 v27, v12, v13
	v_cvt_pk_bf16_f32 v28, v14, v15
	v_cvt_pk_bf16_f32 v29, v16, v17
	v_add_u32_e32 v9, 0x8000, v9
	global_store_dwordx4 v9, v[26:29], s[70:71]
	s_nop 1
	ds_read_b32 v10, v3 offset:64
	ds_read_b32 v11, v3 offset:196
	ds_read_b32 v12, v3 offset:328
	ds_read_b32 v13, v3 offset:460
	ds_read_b32 v14, v3 offset:592
	ds_read_b32 v15, v3 offset:724
	ds_read_b32 v16, v3 offset:856
	ds_read_b32 v17, v3 offset:988
	s_waitcnt lgkmcnt(0)
	v_mul_f32_e32 v10, v10, v96
	v_mul_f32_e32 v11, v11, v97
	v_mul_f32_e32 v12, v12, v98
	v_mul_f32_e32 v13, v13, v99
	v_mul_f32_e32 v14, v14, v100
	v_mul_f32_e32 v15, v15, v101
	v_mul_f32_e32 v16, v16, v102
	v_mul_f32_e32 v17, v17, v103
	v_cvt_pk_bf16_f32 v26, v10, v11
	v_cvt_pk_bf16_f32 v27, v12, v13
	v_cvt_pk_bf16_f32 v28, v14, v15
	v_cvt_pk_bf16_f32 v29, v16, v17
	v_add_u32_e32 v9, 0x8000, v9
	global_store_dwordx4 v9, v[26:29], s[70:71]
	s_nop 1
	ds_read_b32 v10, v3 offset:96
	ds_read_b32 v11, v3 offset:228
	ds_read_b32 v12, v3 offset:360
	ds_read_b32 v13, v3 offset:492
	ds_read_b32 v14, v3 offset:624
	ds_read_b32 v15, v3 offset:756
	ds_read_b32 v16, v3 offset:888
	ds_read_b32 v17, v3 offset:1020
	s_waitcnt lgkmcnt(0)
	v_mul_f32_e32 v10, v10, v96
	v_mul_f32_e32 v11, v11, v97
	v_mul_f32_e32 v12, v12, v98
	v_mul_f32_e32 v13, v13, v99
	v_mul_f32_e32 v14, v14, v100
	v_mul_f32_e32 v15, v15, v101
	v_mul_f32_e32 v16, v16, v102
	v_mul_f32_e32 v17, v17, v103
	v_cvt_pk_bf16_f32 v26, v10, v11
	v_cvt_pk_bf16_f32 v27, v12, v13
	v_cvt_pk_bf16_f32 v28, v14, v15
	v_cvt_pk_bf16_f32 v29, v16, v17
	v_add_u32_e32 v9, 0x8000, v9
	global_store_dwordx4 v9, v[26:29], s[70:71]
	s_nop 1
	s_waitcnt vmcnt(0)
	s_waitcnt lgkmcnt(0)
	ds_write_b32 v2, v64 offset:0
	ds_write_b32 v2, v65 offset:264
	ds_write_b32 v2, v66 offset:528
	ds_write_b32 v2, v67 offset:792
	ds_write_b32 v2, v68 offset:1056
	ds_write_b32 v2, v69 offset:1320
	ds_write_b32 v2, v70 offset:1584
	ds_write_b32 v2, v71 offset:1848
	ds_write_b32 v2, v72 offset:2112
	ds_write_b32 v2, v73 offset:2376
	ds_write_b32 v2, v74 offset:2640
	ds_write_b32 v2, v75 offset:2904
	ds_write_b32 v2, v76 offset:3168
	ds_write_b32 v2, v77 offset:3432
	ds_write_b32 v2, v78 offset:3696
	ds_write_b32 v2, v79 offset:3960
	ds_write_b32 v2, v80 offset:4224
	ds_write_b32 v2, v81 offset:4488
	ds_write_b32 v2, v82 offset:4752
	ds_write_b32 v2, v83 offset:5016
	ds_write_b32 v2, v84 offset:5280
	ds_write_b32 v2, v85 offset:5544
	ds_write_b32 v2, v86 offset:5808
	ds_write_b32 v2, v87 offset:6072
	ds_write_b32 v2, v88 offset:6336
	ds_write_b32 v2, v89 offset:6600
	ds_write_b32 v2, v90 offset:6864
	ds_write_b32 v2, v91 offset:7128
	ds_write_b32 v2, v92 offset:7392
	ds_write_b32 v2, v93 offset:7656
	ds_write_b32 v2, v94 offset:7920
	ds_write_b32 v2, v95 offset:8184
	s_lshr_b32 s70, s67, 2
	s_lshl_b32 s70, s70, 8
	s_and_b32 s71, s67, 3
	s_lshl_b32 s71, s71, 5
	s_add_i32 s70, s70, s71
	s_add_i32 s70, s70, s40
	s_lshl_b32 s70, s70, 12
	s_lshl_b32 s71, s55, 7
	s_add_i32 s70, s70, s71
	s_add_u32 s70, s70, 0x2200000
	s_add_u32 s70, s26, s70
	s_addc_u32 s71, s27, 0
	s_waitcnt lgkmcnt(0)
	ds_read_b32 v10, v3 offset:0
	ds_read_b32 v11, v3 offset:132
	ds_read_b32 v12, v3 offset:264
	ds_read_b32 v13, v3 offset:396
	ds_read_b32 v14, v3 offset:528
	ds_read_b32 v15, v3 offset:660
	ds_read_b32 v16, v3 offset:792
	ds_read_b32 v17, v3 offset:924
	s_waitcnt lgkmcnt(0)
	v_mul_f32_e32 v10, v10, v104
	v_mul_f32_e32 v11, v11, v105
	v_mul_f32_e32 v12, v12, v106
	v_mul_f32_e32 v13, v13, v107
	v_mul_f32_e32 v14, v14, v108
	v_mul_f32_e32 v15, v15, v109
	v_mul_f32_e32 v16, v16, v110
	v_mul_f32_e32 v17, v17, v111
	v_cvt_pk_bf16_f32 v26, v10, v11
	v_cvt_pk_bf16_f32 v27, v12, v13
	v_cvt_pk_bf16_f32 v28, v14, v15
	v_cvt_pk_bf16_f32 v29, v16, v17
	v_mov_b32_e32 v9, v4
	global_store_dwordx4 v9, v[26:29], s[70:71]
	s_nop 1
	ds_read_b32 v10, v3 offset:32
	ds_read_b32 v11, v3 offset:164
	ds_read_b32 v12, v3 offset:296
	ds_read_b32 v13, v3 offset:428
	ds_read_b32 v14, v3 offset:560
	ds_read_b32 v15, v3 offset:692
	ds_read_b32 v16, v3 offset:824
	ds_read_b32 v17, v3 offset:956
	s_waitcnt lgkmcnt(0)
	v_mul_f32_e32 v10, v10, v104
	v_mul_f32_e32 v11, v11, v105
	v_mul_f32_e32 v12, v12, v106
	v_mul_f32_e32 v13, v13, v107
	v_mul_f32_e32 v14, v14, v108
	v_mul_f32_e32 v15, v15, v109
	v_mul_f32_e32 v16, v16, v110
	v_mul_f32_e32 v17, v17, v111
	v_cvt_pk_bf16_f32 v26, v10, v11
	v_cvt_pk_bf16_f32 v27, v12, v13
	v_cvt_pk_bf16_f32 v28, v14, v15
	v_cvt_pk_bf16_f32 v29, v16, v17
	v_add_u32_e32 v9, 0x8000, v9
	global_store_dwordx4 v9, v[26:29], s[70:71]
	s_nop 1
	ds_read_b32 v10, v3 offset:64
	ds_read_b32 v11, v3 offset:196
	ds_read_b32 v12, v3 offset:328
	ds_read_b32 v13, v3 offset:460
	ds_read_b32 v14, v3 offset:592
	ds_read_b32 v15, v3 offset:724
	ds_read_b32 v16, v3 offset:856
	ds_read_b32 v17, v3 offset:988
	s_waitcnt lgkmcnt(0)
	v_mul_f32_e32 v10, v10, v104
	v_mul_f32_e32 v11, v11, v105
	v_mul_f32_e32 v12, v12, v106
	v_mul_f32_e32 v13, v13, v107
	v_mul_f32_e32 v14, v14, v108
	v_mul_f32_e32 v15, v15, v109
	v_mul_f32_e32 v16, v16, v110
	v_mul_f32_e32 v17, v17, v111
	v_cvt_pk_bf16_f32 v26, v10, v11
	v_cvt_pk_bf16_f32 v27, v12, v13
	v_cvt_pk_bf16_f32 v28, v14, v15
	v_cvt_pk_bf16_f32 v29, v16, v17
	v_add_u32_e32 v9, 0x8000, v9
	global_store_dwordx4 v9, v[26:29], s[70:71]
	s_nop 1
	ds_read_b32 v10, v3 offset:96
	ds_read_b32 v11, v3 offset:228
	ds_read_b32 v12, v3 offset:360
	ds_read_b32 v13, v3 offset:492
	ds_read_b32 v14, v3 offset:624
	ds_read_b32 v15, v3 offset:756
	ds_read_b32 v16, v3 offset:888
	ds_read_b32 v17, v3 offset:1020
	s_waitcnt lgkmcnt(0)
	v_mul_f32_e32 v10, v10, v104
	v_mul_f32_e32 v11, v11, v105
	v_mul_f32_e32 v12, v12, v106
	v_mul_f32_e32 v13, v13, v107
	v_mul_f32_e32 v14, v14, v108
	v_mul_f32_e32 v15, v15, v109
	v_mul_f32_e32 v16, v16, v110
	v_mul_f32_e32 v17, v17, v111
	v_cvt_pk_bf16_f32 v26, v10, v11
	v_cvt_pk_bf16_f32 v27, v12, v13
	v_cvt_pk_bf16_f32 v28, v14, v15
	v_cvt_pk_bf16_f32 v29, v16, v17
	v_add_u32_e32 v9, 0x8000, v9
	global_store_dwordx4 v9, v[26:29], s[70:71]
	s_nop 1
	s_waitcnt vmcnt(0) lgkmcnt(0)
.Lmy_cv1_end:
	v_cmp_eq_u32_e32 vcc, 0, v208
	s_nop 3
	s_and_saveexec_b64 s[0:1], vcc
	s_cbranch_execz .LBB0_391
	v_mov_b32_e32 v0, s88
	s_waitcnt vmcnt(0) expcnt(0) lgkmcnt(0)
	ds_read_b32 v2, v0
	ds_read_b32 v0, v0 offset:4
	s_waitcnt lgkmcnt(1)
	v_cmp_ne_u32_e32 vcc, 0, v2
	s_cbranch_vccnz .LBB0_359
	s_add_u32 s4, s26, 0xfc00200
	s_addc_u32 s5, s27, 0
	s_add_u32 s16, s26, 0xfc00400
	s_addc_u32 s17, s27, 0
	s_add_u32 s20, s26, 0xfc00500
	s_addc_u32 s21, s27, 0
	s_add_u32 s36, s26, 0xfc00600
	s_addc_u32 s37, s27, 0
	s_add_u32 s40, s26, 0xfc00700
	s_addc_u32 s41, s27, 0
	s_add_u32 s56, s26, 0xfc00800
	s_addc_u32 s57, s27, 0
	s_add_u32 s58, s26, 0xfc00900
	s_addc_u32 s59, s27, 0
	s_add_u32 s60, s26, 0xfc00a00
	s_addc_u32 s61, s27, 0
	s_add_u32 s62, s26, 0xfc00b00
	s_addc_u32 s63, s27, 0
	s_add_u32 s64, s26, 0xfc00c00
	s_addc_u32 s65, s27, 0
	s_add_u32 s66, s26, 0xfc00d00
	s_addc_u32 s67, s27, 0
	s_add_u32 s68, s26, 0xfc00e00
	s_addc_u32 s69, s27, 0
	s_add_u32 s70, s26, 0xfc00f00
	s_addc_u32 s71, s27, 0
	s_add_u32 s72, s26, 0xfc01000
	s_addc_u32 s73, s27, 0
	s_add_u32 s74, s26, 0xfc01100
	s_addc_u32 s75, s27, 0
	s_add_u32 s76, s26, 0xfc01200
	s_addc_u32 s77, s27, 0
	s_mul_i32 s3, s31, s94
	s_add_u32 s78, s26, 0xfc01300
	s_mul_i32 s3, s3, s30
	s_addc_u32 s79, s27, 0
	s_mov_b32 s87, 1
	v_mov_b32_e32 v16, 0
	s_branch .LBB0_345

.LBB0_475:
	s_cmp_gt_u32 s29, 4
	s_cselect_b64 s[0:1], -1, 0
	s_and_b64 s[0:1], s[36:37], s[0:1]
	s_andn2_b64 vcc, exec, s[0:1]
	s_cbranch_vccnz .LBB0_525
	s_waitcnt vmcnt(0)
	v_cmp_eq_u32_e32 vcc, 0, v208
	s_waitcnt vmcnt(0) lgkmcnt(0)
	s_barrier
	v_readfirstlane_b32 s3, v208
	s_nop 3
	s_lshr_b32 s3, s3, 6
	s_cmp_eq_u32 s3, 0
	s_cbranch_scc1 .Lmy_cv2_end
	v_readlane_b32 s36, v237, 0
	v_readlane_b32 s37, v237, 1
	s_mul_i32 s4, s2, 7
	s_add_i32 s4, s4, s3
	s_add_i32 s66, s4, 7679
	s_lshl_b32 s72, s3, 14
	s_nop 4
	s_load_dwordx4 s[60:63], s[36:37], 0x60
	s_load_dwordx2 s[64:65], s[36:37], 0x70
	v_lshrrev_b32_e32 v6, 5, v209
	v_and_b32_e32 v7, 31, v209
	v_mul_u32_u24_e32 v0, 0x1600, v6
	v_add_lshl_u32 v0, v0, v7, 2
	v_mul_u32_u24_e32 v2, 33, v6
	v_add_lshl_u32 v2, v2, v7, 2
	v_add_u32_e32 v2, s72, v2
	v_and_b32_e32 v8, 7, v209
	v_lshrrev_b32_e32 v9, 3, v209
	v_mul_u32_u24_e32 v3, 0x108, v8
	v_add_lshl_u32 v3, v3, v9, 2
	v_add_u32_e32 v3, s72, v3
	v_lshlrev_b32_e32 v4, 12, v9
	v_lshl_add_u32 v4, v8, 4, v4
	v_lshlrev_b32_e32 v5, 5, v8
	s_waitcnt lgkmcnt(0)
	s_cmpk_ge_u32 s66, 0x1600
	s_cselect_b32 s68, s64, s62
	s_cselect_b32 s69, s65, s63
	s_cselect_b32 s54, 128, 0
	s_cselect_b32 s41, 0x1600, 0
	s_sub_u32 s41, s66, s41
	s_mul_hi_u32 s4, s41, 0xba2e8ba3
	s_lshr_b32 s4, s4, 7
	s_mul_i32 s70, s4, 0xb0
	s_sub_u32 s5, s41, s70
	s_mul_i32 s70, s4, 0x160000
	s_lshl_b32 s71, s5, 7
	s_add_u32 s68, s68, s70
	s_addc_u32 s69, s69, 0
	s_add_u32 s68, s68, s71
	s_addc_u32 s69, s69, 0
	v_mov_b32_e32 v1, v0
	global_load_dword v32, v1, s[68:69] nt
	v_add_u32_e32 v1, 0xb000, v1
	global_load_dword v33, v1, s[68:69] nt
	v_add_u32_e32 v1, 0xb000, v1
	global_load_dword v34, v1, s[68:69] nt
	v_add_u32_e32 v1, 0xb000, v1
	global_load_dword v35, v1, s[68:69] nt
	v_add_u32_e32 v1, 0xb000, v1
	global_load_dword v36, v1, s[68:69] nt
	v_add_u32_e32 v1, 0xb000, v1
	global_load_dword v37, v1, s[68:69] nt
	v_add_u32_e32 v1, 0xb000, v1
	global_load_dword v38, v1, s[68:69] nt
	v_add_u32_e32 v1, 0xb000, v1
	global_load_dword v39, v1, s[68:69] nt
	v_add_u32_e32 v1, 0xb000, v1
	global_load_dword v40, v1, s[68:69] nt
	v_add_u32_e32 v1, 0xb000, v1
	global_load_dword v41, v1, s[68:69] nt
	v_add_u32_e32 v1, 0xb000, v1
	global_load_dword v42, v1, s[68:69] nt
	v_add_u32_e32 v1, 0xb000, v1
	global_load_dword v43, v1, s[68:69] nt
	v_add_u32_e32 v1, 0xb000, v1
	global_load_dword v44, v1, s[68:69] nt
	v_add_u32_e32 v1, 0xb000, v1
	global_load_dword v45, v1, s[68:69] nt
	v_add_u32_e32 v1, 0xb000, v1
	global_load_dword v46, v1, s[68:69] nt
	v_add_u32_e32 v1, 0xb000, v1
	global_load_dword v47, v1, s[68:69] nt
	v_add_u32_e32 v1, 0xb000, v1
	global_load_dword v48, v1, s[68:69] nt
	v_add_u32_e32 v1, 0xb000, v1
	global_load_dword v49, v1, s[68:69] nt
	v_add_u32_e32 v1, 0xb000, v1
	global_load_dword v50, v1, s[68:69] nt
	v_add_u32_e32 v1, 0xb000, v1
	global_load_dword v51, v1, s[68:69] nt
	v_add_u32_e32 v1, 0xb000, v1
	global_load_dword v52, v1, s[68:69] nt
	v_add_u32_e32 v1, 0xb000, v1
	global_load_dword v53, v1, s[68:69] nt
	v_add_u32_e32 v1, 0xb000, v1
	global_load_dword v54, v1, s[68:69] nt
	v_add_u32_e32 v1, 0xb000, v1
	global_load_dword v55, v1, s[68:69] nt
	v_add_u32_e32 v1, 0xb000, v1
	global_load_dword v56, v1, s[68:69] nt
	v_add_u32_e32 v1, 0xb000, v1
	global_load_dword v57, v1, s[68:69] nt
	v_add_u32_e32 v1, 0xb000, v1
	global_load_dword v58, v1, s[68:69] nt
	v_add_u32_e32 v1, 0xb000, v1
	global_load_dword v59, v1, s[68:69] nt
	v_add_u32_e32 v1, 0xb000, v1
	global_load_dword v60, v1, s[68:69] nt
	v_add_u32_e32 v1, 0xb000, v1
	global_load_dword v61, v1, s[68:69] nt
	v_add_u32_e32 v1, 0xb000, v1
	global_load_dword v62, v1, s[68:69] nt
	v_add_u32_e32 v1, 0xb000, v1
	global_load_dword v63, v1, s[68:69] nt
	s_lshl_b32 s70, s4, 8
	s_add_u32 s70, s60, s70
	s_addc_u32 s71, s61, 0
	global_load_dwordx4 v[96:99], v5, s[70:71]
	global_load_dwordx4 v[100:103], v5, s[70:71] offset:16
	s_addk_i32 s66, 0x700
	s_cmpk_ge_u32 s66, 0x1600
	s_cselect_b32 s68, s64, s62
	s_cselect_b32 s69, s65, s63
	s_cselect_b32 s40, 128, 0
	s_cselect_b32 s41, 0x1600, 0
	s_sub_u32 s41, s66, s41
	s_mul_hi_u32 s55, s41, 0xba2e8ba3
	s_lshr_b32 s55, s55, 7
	s_mul_i32 s70, s55, 0xb0
	s_sub_u32 s67, s41, s70
	s_mul_i32 s70, s55, 0x160000
	s_lshl_b32 s71, s67, 7
	s_add_u32 s68, s68, s70
	s_addc_u32 s69, s69, 0
	s_add_u32 s68, s68, s71
	s_addc_u32 s69, s69, 0
	v_mov_b32_e32 v1, v0
	global_load_dword v64, v1, s[68:69] nt
	v_add_u32_e32 v1, 0xb000, v1
	global_load_dword v65, v1, s[68:69] nt
	v_add_u32_e32 v1, 0xb000, v1
	global_load_dword v66, v1, s[68:69] nt
	v_add_u32_e32 v1, 0xb000, v1
	global_load_dword v67, v1, s[68:69] nt
	v_add_u32_e32 v1, 0xb000, v1
	global_load_dword v68, v1, s[68:69] nt
	v_add_u32_e32 v1, 0xb000, v1
	global_load_dword v69, v1, s[68:69] nt
	v_add_u32_e32 v1, 0xb000, v1
	global_load_dword v70, v1, s[68:69] nt
	v_add_u32_e32 v1, 0xb000, v1
	global_load_dword v71, v1, s[68:69] nt
	v_add_u32_e32 v1, 0xb000, v1
	global_load_dword v72, v1, s[68:69] nt
	v_add_u32_e32 v1, 0xb000, v1
	global_load_dword v73, v1, s[68:69] nt
	v_add_u32_e32 v1, 0xb000, v1
	global_load_dword v74, v1, s[68:69] nt
	v_add_u32_e32 v1, 0xb000, v1
	global_load_dword v75, v1, s[68:69] nt
	v_add_u32_e32 v1, 0xb000, v1
	global_load_dword v76, v1, s[68:69] nt
	v_add_u32_e32 v1, 0xb000, v1
	global_load_dword v77, v1, s[68:69] nt
	v_add_u32_e32 v1, 0xb000, v1
	global_load_dword v78, v1, s[68:69] nt
	v_add_u32_e32 v1, 0xb000, v1
	global_load_dword v79, v1, s[68:69] nt
	v_add_u32_e32 v1, 0xb000, v1
	global_load_dword v80, v1, s[68:69] nt
	v_add_u32_e32 v1, 0xb000, v1
	global_load_dword v81, v1, s[68:69] nt
	v_add_u32_e32 v1, 0xb000, v1
	global_load_dword v82, v1, s[68:69] nt
	v_add_u32_e32 v1, 0xb000, v1
	global_load_dword v83, v1, s[68:69] nt
	v_add_u32_e32 v1, 0xb000, v1
	global_load_dword v84, v1, s[68:69] nt
	v_add_u32_e32 v1, 0xb000, v1
	global_load_dword v85, v1, s[68:69] nt
	v_add_u32_e32 v1, 0xb000, v1
	global_load_dword v86, v1, s[68:69] nt
	v_add_u32_e32 v1, 0xb000, v1
	global_load_dword v87, v1, s[68:69] nt
	v_add_u32_e32 v1, 0xb000, v1
	global_load_dword v88, v1, s[68:69] nt
	v_add_u32_e32 v1, 0xb000, v1
	global_load_dword v89, v1, s[68:69] nt
	v_add_u32_e32 v1, 0xb000, v1
	global_load_dword v90, v1, s[68:69] nt
	v_add_u32_e32 v1, 0xb000, v1
	global_load_dword v91, v1, s[68:69] nt
	v_add_u32_e32 v1, 0xb000, v1
	global_load_dword v92, v1, s[68:69] nt
	v_add_u32_e32 v1, 0xb000, v1
	global_load_dword v93, v1, s[68:69] nt
	v_add_u32_e32 v1, 0xb000, v1
	global_load_dword v94, v1, s[68:69] nt
	v_add_u32_e32 v1, 0xb000, v1
	global_load_dword v95, v1, s[68:69] nt
	s_lshl_b32 s70, s55, 8
	s_add_u32 s70, s60, s70
	s_addc_u32 s71, s61, 0
	global_load_dwordx4 v[104:107], v5, s[70:71]
	global_load_dwordx4 v[108:111], v5, s[70:71] offset:16
	s_waitcnt vmcnt(34)
	ds_write_b32 v2, v32 offset:0
	ds_write_b32 v2, v33 offset:264
	ds_write_b32 v2, v34 offset:528
	ds_write_b32 v2, v35 offset:792
	ds_write_b32 v2, v36 offset:1056
	ds_write_b32 v2, v37 offset:1320
	ds_write_b32 v2, v38 offset:1584
	ds_write_b32 v2, v39 offset:1848
	ds_write_b32 v2, v40 offset:2112
	ds_write_b32 v2, v41 offset:2376
	ds_write_b32 v2, v42 offset:2640
	ds_write_b32 v2, v43 offset:2904
	ds_write_b32 v2, v44 offset:3168
	ds_write_b32 v2, v45 offset:3432
	ds_write_b32 v2, v46 offset:3696
	ds_write_b32 v2, v47 offset:3960
	ds_write_b32 v2, v48 offset:4224
	ds_write_b32 v2, v49 offset:4488
	ds_write_b32 v2, v50 offset:4752
	ds_write_b32 v2, v51 offset:5016
	ds_write_b32 v2, v52 offset:5280
	ds_write_b32 v2, v53 offset:5544
	ds_write_b32 v2, v54 offset:5808
	ds_write_b32 v2, v55 offset:6072
	ds_write_b32 v2, v56 offset:6336
	ds_write_b32 v2, v57 offset:6600
	ds_write_b32 v2, v58 offset:6864
	ds_write_b32 v2, v59 offset:7128
	ds_write_b32 v2, v60 offset:7392
	ds_write_b32 v2, v61 offset:7656
	ds_write_b32 v2, v62 offset:7920
	ds_write_b32 v2, v63 offset:8184
	s_lshr_b32 s70, s5, 2
	s_lshl_b32 s70, s70, 8
	s_and_b32 s71, s5, 3
	s_lshl_b32 s71, s71, 5
	s_add_i32 s70, s70, s71
	s_add_i32 s70, s70, s54
	s_lshl_b32 s70, s70, 12
	s_lshl_b32 s71, s4, 7
	s_add_i32 s70, s70, s71
	s_add_u32 s70, s70, 0x2200000
	s_add_u32 s70, s26, s70
	s_addc_u32 s71, s27, 0
	s_waitcnt lgkmcnt(0)
	ds_read_b32 v10, v3 offset:0
	ds_read_b32 v11, v3 offset:132
	ds_read_b32 v12, v3 offset:264
	ds_read_b32 v13, v3 offset:396
	ds_read_b32 v14, v3 offset:528
	ds_read_b32 v15, v3 offset:660
	ds_read_b32 v16, v3 offset:792
	ds_read_b32 v17, v3 offset:924
	s_waitcnt lgkmcnt(0)
	v_mul_f32_e32 v10, v10, v96
	v_mul_f32_e32 v11, v11, v97
	v_mul_f32_e32 v12, v12, v98
	v_mul_f32_e32 v13, v13, v99
	v_mul_f32_e32 v14, v14, v100
	v_mul_f32_e32 v15, v15, v101
	v_mul_f32_e32 v16, v16, v102
	v_mul_f32_e32 v17, v17, v103
	v_cvt_pk_bf16_f32 v26, v10, v11
	v_cvt_pk_bf16_f32 v27, v12, v13
	v_cvt_pk_bf16_f32 v28, v14, v15
	v_cvt_pk_bf16_f32 v29, v16, v17
	v_mov_b32_e32 v9, v4
	global_store_dwordx4 v9, v[26:29], s[70:71]
	s_nop 1
	ds_read_b32 v10, v3 offset:32
	ds_read_b32 v11, v3 offset:164
	ds_read_b32 v12, v3 offset:296
	ds_read_b32 v13, v3 offset:428
	ds_read_b32 v14, v3 offset:560
	ds_read_b32 v15, v3 offset:692
	ds_read_b32 v16, v3 offset:824
	ds_read_b32 v17, v3 offset:956
	s_waitcnt lgkmcnt(0)
	v_mul_f32_e32 v10, v10, v96
	v_mul_f32_e32 v11, v11, v97
	v_mul_f32_e32 v12, v12, v98
	v_mul_f32_e32 v13, v13, v99
	v_mul_f32_e32 v14, v14, v100
	v_mul_f32_e32 v15, v15, v101
	v_mul_f32_e32 v16, v16, v102
	v_mul_f32_e32 v17, v17, v103
	v_cvt_pk_bf16_f32 v26, v10, v11
	v_cvt_pk_bf16_f32 v27, v12, v13
	v_cvt_pk_bf16_f32 v28, v14, v15
	v_cvt_pk_bf16_f32 v29, v16, v17
	v_add_u32_e32 v9, 0x8000, v9
	global_store_dwordx4 v9, v[26:29], s[70:71]
	s_nop 1
	ds_read_b32 v10, v3 offset:64
	ds_read_b32 v11, v3 offset:196
	ds_read_b32 v12, v3 offset:328
	ds_read_b32 v13, v3 offset:460
	ds_read_b32 v14, v3 offset:592
	ds_read_b32 v15, v3 offset:724
	ds_read_b32 v16, v3 offset:856
	ds_read_b32 v17, v3 offset:988
	s_waitcnt lgkmcnt(0)
	v_mul_f32_e32 v10, v10, v96
	v_mul_f32_e32 v11, v11, v97
	v_mul_f32_e32 v12, v12, v98
	v_mul_f32_e32 v13, v13, v99
	v_mul_f32_e32 v14, v14, v100
	v_mul_f32_e32 v15, v15, v101
	v_mul_f32_e32 v16, v16, v102
	v_mul_f32_e32 v17, v17, v103
	v_cvt_pk_bf16_f32 v26, v10, v11
	v_cvt_pk_bf16_f32 v27, v12, v13
	v_cvt_pk_bf16_f32 v28, v14, v15
	v_cvt_pk_bf16_f32 v29, v16, v17
	v_add_u32_e32 v9, 0x8000, v9
	global_store_dwordx4 v9, v[26:29], s[70:71]
	s_nop 1
	ds_read_b32 v10, v3 offset:96
	ds_read_b32 v11, v3 offset:228
	ds_read_b32 v12, v3 offset:360
	ds_read_b32 v13, v3 offset:492
	ds_read_b32 v14, v3 offset:624
	ds_read_b32 v15, v3 offset:756
	ds_read_b32 v16, v3 offset:888
	ds_read_b32 v17, v3 offset:1020
	s_waitcnt lgkmcnt(0)
	v_mul_f32_e32 v10, v10, v96
	v_mul_f32_e32 v11, v11, v97
	v_mul_f32_e32 v12, v12, v98
	v_mul_f32_e32 v13, v13, v99
	v_mul_f32_e32 v14, v14, v100
	v_mul_f32_e32 v15, v15, v101
	v_mul_f32_e32 v16, v16, v102
	v_mul_f32_e32 v17, v17, v103
	v_cvt_pk_bf16_f32 v26, v10, v11
	v_cvt_pk_bf16_f32 v27, v12, v13
	v_cvt_pk_bf16_f32 v28, v14, v15
	v_cvt_pk_bf16_f32 v29, v16, v17
	v_add_u32_e32 v9, 0x8000, v9
	global_store_dwordx4 v9, v[26:29], s[70:71]
	s_nop 1
	s_waitcnt vmcnt(0)
	s_waitcnt lgkmcnt(0)
	ds_write_b32 v2, v64 offset:0
	ds_write_b32 v2, v65 offset:264
	ds_write_b32 v2, v66 offset:528
	ds_write_b32 v2, v67 offset:792
	ds_write_b32 v2, v68 offset:1056
	ds_write_b32 v2, v69 offset:1320
	ds_write_b32 v2, v70 offset:1584
	ds_write_b32 v2, v71 offset:1848
	ds_write_b32 v2, v72 offset:2112
	ds_write_b32 v2, v73 offset:2376
	ds_write_b32 v2, v74 offset:2640
	ds_write_b32 v2, v75 offset:2904
	ds_write_b32 v2, v76 offset:3168
	ds_write_b32 v2, v77 offset:3432
	ds_write_b32 v2, v78 offset:3696
	ds_write_b32 v2, v79 offset:3960
	ds_write_b32 v2, v80 offset:4224
	ds_write_b32 v2, v81 offset:4488
	ds_write_b32 v2, v82 offset:4752
	ds_write_b32 v2, v83 offset:5016
	ds_write_b32 v2, v84 offset:5280
	ds_write_b32 v2, v85 offset:5544
	ds_write_b32 v2, v86 offset:5808
	ds_write_b32 v2, v87 offset:6072
	ds_write_b32 v2, v88 offset:6336
	ds_write_b32 v2, v89 offset:6600
	ds_write_b32 v2, v90 offset:6864
	ds_write_b32 v2, v91 offset:7128
	ds_write_b32 v2, v92 offset:7392
	ds_write_b32 v2, v93 offset:7656
	ds_write_b32 v2, v94 offset:7920
	ds_write_b32 v2, v95 offset:8184
	s_lshr_b32 s70, s67, 2
	s_lshl_b32 s70, s70, 8
	s_and_b32 s71, s67, 3
	s_lshl_b32 s71, s71, 5
	s_add_i32 s70, s70, s71
	s_add_i32 s70, s70, s40
	s_lshl_b32 s70, s70, 12
	s_lshl_b32 s71, s55, 7
	s_add_i32 s70, s70, s71
	s_add_u32 s70, s70, 0x2200000
	s_add_u32 s70, s26, s70
	s_addc_u32 s71, s27, 0
	s_waitcnt lgkmcnt(0)
	ds_read_b32 v10, v3 offset:0
	ds_read_b32 v11, v3 offset:132
	ds_read_b32 v12, v3 offset:264
	ds_read_b32 v13, v3 offset:396
	ds_read_b32 v14, v3 offset:528
	ds_read_b32 v15, v3 offset:660
	ds_read_b32 v16, v3 offset:792
	ds_read_b32 v17, v3 offset:924
	s_waitcnt lgkmcnt(0)
	v_mul_f32_e32 v10, v10, v104
	v_mul_f32_e32 v11, v11, v105
	v_mul_f32_e32 v12, v12, v106
	v_mul_f32_e32 v13, v13, v107
	v_mul_f32_e32 v14, v14, v108
	v_mul_f32_e32 v15, v15, v109
	v_mul_f32_e32 v16, v16, v110
	v_mul_f32_e32 v17, v17, v111
	v_cvt_pk_bf16_f32 v26, v10, v11
	v_cvt_pk_bf16_f32 v27, v12, v13
	v_cvt_pk_bf16_f32 v28, v14, v15
	v_cvt_pk_bf16_f32 v29, v16, v17
	v_mov_b32_e32 v9, v4
	global_store_dwordx4 v9, v[26:29], s[70:71]
	s_nop 1
	ds_read_b32 v10, v3 offset:32
	ds_read_b32 v11, v3 offset:164
	ds_read_b32 v12, v3 offset:296
	ds_read_b32 v13, v3 offset:428
	ds_read_b32 v14, v3 offset:560
	ds_read_b32 v15, v3 offset:692
	ds_read_b32 v16, v3 offset:824
	ds_read_b32 v17, v3 offset:956
	s_waitcnt lgkmcnt(0)
	v_mul_f32_e32 v10, v10, v104
	v_mul_f32_e32 v11, v11, v105
	v_mul_f32_e32 v12, v12, v106
	v_mul_f32_e32 v13, v13, v107
	v_mul_f32_e32 v14, v14, v108
	v_mul_f32_e32 v15, v15, v109
	v_mul_f32_e32 v16, v16, v110
	v_mul_f32_e32 v17, v17, v111
	v_cvt_pk_bf16_f32 v26, v10, v11
	v_cvt_pk_bf16_f32 v27, v12, v13
	v_cvt_pk_bf16_f32 v28, v14, v15
	v_cvt_pk_bf16_f32 v29, v16, v17
	v_add_u32_e32 v9, 0x8000, v9
	global_store_dwordx4 v9, v[26:29], s[70:71]
	s_nop 1
	ds_read_b32 v10, v3 offset:64
	ds_read_b32 v11, v3 offset:196
	ds_read_b32 v12, v3 offset:328
	ds_read_b32 v13, v3 offset:460
	ds_read_b32 v14, v3 offset:592
	ds_read_b32 v15, v3 offset:724
	ds_read_b32 v16, v3 offset:856
	ds_read_b32 v17, v3 offset:988
	s_waitcnt lgkmcnt(0)
	v_mul_f32_e32 v10, v10, v104
	v_mul_f32_e32 v11, v11, v105
	v_mul_f32_e32 v12, v12, v106
	v_mul_f32_e32 v13, v13, v107
	v_mul_f32_e32 v14, v14, v108
	v_mul_f32_e32 v15, v15, v109
	v_mul_f32_e32 v16, v16, v110
	v_mul_f32_e32 v17, v17, v111
	v_cvt_pk_bf16_f32 v26, v10, v11
	v_cvt_pk_bf16_f32 v27, v12, v13
	v_cvt_pk_bf16_f32 v28, v14, v15
	v_cvt_pk_bf16_f32 v29, v16, v17
	v_add_u32_e32 v9, 0x8000, v9
	global_store_dwordx4 v9, v[26:29], s[70:71]
	s_nop 1
	ds_read_b32 v10, v3 offset:96
	ds_read_b32 v11, v3 offset:228
	ds_read_b32 v12, v3 offset:360
	ds_read_b32 v13, v3 offset:492
	ds_read_b32 v14, v3 offset:624
	ds_read_b32 v15, v3 offset:756
	ds_read_b32 v16, v3 offset:888
	ds_read_b32 v17, v3 offset:1020
	s_waitcnt lgkmcnt(0)
	v_mul_f32_e32 v10, v10, v104
	v_mul_f32_e32 v11, v11, v105
	v_mul_f32_e32 v12, v12, v106
	v_mul_f32_e32 v13, v13, v107
	v_mul_f32_e32 v14, v14, v108
	v_mul_f32_e32 v15, v15, v109
	v_mul_f32_e32 v16, v16, v110
	v_mul_f32_e32 v17, v17, v111
	v_cvt_pk_bf16_f32 v26, v10, v11
	v_cvt_pk_bf16_f32 v27, v12, v13
	v_cvt_pk_bf16_f32 v28, v14, v15
	v_cvt_pk_bf16_f32 v29, v16, v17
	v_add_u32_e32 v9, 0x8000, v9
	global_store_dwordx4 v9, v[26:29], s[70:71]
	s_nop 1
	s_waitcnt vmcnt(0) lgkmcnt(0)
.Lmy_cv2_end:
	v_cmp_eq_u32_e32 vcc, 0, v208
	s_nop 3
	s_and_saveexec_b64 s[0:1], vcc
	s_cbranch_execz .LBB0_524
	v_mov_b32_e32 v0, s88
	s_waitcnt vmcnt(0) expcnt(0) lgkmcnt(0)
	ds_read_b32 v2, v0
	ds_read_b32 v0, v0 offset:4
	s_waitcnt lgkmcnt(1)
	v_cmp_ne_u32_e32 vcc, 0, v2
	s_cbranch_vccnz .LBB0_492
	s_add_u32 s4, s26, 0xfc00200
	s_addc_u32 s5, s27, 0
	s_add_u32 s8, s26, 0xfc00400
	s_addc_u32 s9, s27, 0
	s_add_u32 s12, s26, 0xfc00500
	s_addc_u32 s13, s27, 0
	s_add_u32 s36, s26, 0xfc00600
	s_addc_u32 s37, s27, 0
	s_add_u32 s38, s26, 0xfc00700
	s_addc_u32 s39, s27, 0
	s_add_u32 s40, s26, 0xfc00800
	s_addc_u32 s41, s27, 0
	s_add_u32 s42, s26, 0xfc00900
	s_addc_u32 s43, s27, 0
	s_add_u32 s44, s26, 0xfc00a00
	s_addc_u32 s45, s27, 0
	s_add_u32 s46, s26, 0xfc00b00
	s_addc_u32 s47, s27, 0
	s_add_u32 s48, s26, 0xfc00c00
	s_addc_u32 s49, s27, 0
	s_add_u32 s50, s26, 0xfc00d00
	s_addc_u32 s51, s27, 0
	s_add_u32 s54, s26, 0xfc00e00
	s_addc_u32 s55, s27, 0
	s_add_u32 s56, s26, 0xfc00f00
	s_addc_u32 s57, s27, 0
	s_add_u32 s58, s26, 0xfc01000
	s_addc_u32 s59, s27, 0
	s_add_u32 s60, s26, 0xfc01100
	s_addc_u32 s61, s27, 0
	s_add_u32 s62, s26, 0xfc01200
	s_addc_u32 s63, s27, 0
	s_mul_i32 s3, s31, s94
	s_add_u32 s64, s26, 0xfc01300
	s_mul_i32 s3, s3, s30
	s_addc_u32 s65, s27, 0
	s_mov_b32 s72, 1
	v_mov_b32_e32 v16, 0
	s_branch .LBB0_480

	.amdhsa_kernel _Z9block_fwd4Args
		.amdhsa_group_segment_fixed_size 0
		.amdhsa_private_segment_fixed_size 0
		.amdhsa_kernarg_size 408
		.amdhsa_user_sgpr_count 2
		.amdhsa_user_sgpr_dispatch_ptr 0
		.amdhsa_user_sgpr_queue_ptr 0
		.amdhsa_user_sgpr_kernarg_segment_ptr 1
		.amdhsa_user_sgpr_dispatch_id 0
		.amdhsa_user_sgpr_kernarg_preload_length 0
		.amdhsa_user_sgpr_kernarg_preload_offset 0
		.amdhsa_user_sgpr_private_segment_size 0
		.amdhsa_uses_dynamic_stack 0
		.amdhsa_enable_private_segment 0
		.amdhsa_system_sgpr_workgroup_id_x 1
		.amdhsa_system_sgpr_workgroup_id_y 0
		.amdhsa_system_sgpr_workgroup_id_z 0
		.amdhsa_system_sgpr_workgroup_info 0
		.amdhsa_system_vgpr_workitem_id 2
		.amdhsa_next_free_vgpr 240
		.amdhsa_next_free_sgpr 102
		.amdhsa_accum_offset 240
		.amdhsa_reserve_vcc 1
		.amdhsa_float_round_mode_32 0
		.amdhsa_float_round_mode_16_64 0
		.amdhsa_float_denorm_mode_32 3
		.amdhsa_float_denorm_mode_16_64 3
		.amdhsa_dx10_clamp 1
		.amdhsa_ieee_mode 1
		.amdhsa_fp16_overflow 0
		.amdhsa_tg_split 0
		.amdhsa_exception_fp_ieee_invalid_op 0
		.amdhsa_exception_fp_denorm_src 0
		.amdhsa_exception_fp_ieee_div_zero 0
		.amdhsa_exception_fp_ieee_overflow 0
		.amdhsa_exception_fp_ieee_underflow 0
		.amdhsa_exception_fp_ieee_inexact 0
		.amdhsa_exception_int_div_zero 0
	.end_amdhsa_kernel

amdhsa.kernels:
  - .agpr_count:     0
    .args:
      - .offset:         0
        .size:           152
        .value_kind:     by_value
      - .offset:         152
        .size:           4
        .value_kind:     hidden_block_count_x
      - .offset:         156
        .size:           4
        .value_kind:     hidden_block_count_y
      - .offset:         160
        .size:           4
        .value_kind:     hidden_block_count_z
      - .offset:         164
        .size:           2
        .value_kind:     hidden_group_size_x
      - .offset:         166
        .size:           2
        .value_kind:     hidden_group_size_y
      - .offset:         168
        .size:           2
        .value_kind:     hidden_group_size_z
      - .offset:         170
        .size:           2
        .value_kind:     hidden_remainder_x
      - .offset:         172
        .size:           2
        .value_kind:     hidden_remainder_y
      - .offset:         174
        .size:           2
        .value_kind:     hidden_remainder_z
      - .offset:         192
        .size:           8
        .value_kind:     hidden_global_offset_x
      - .offset:         200
        .size:           8
        .value_kind:     hidden_global_offset_y
      - .offset:         208
        .size:           8
        .value_kind:     hidden_global_offset_z
      - .offset:         216
        .size:           2
        .value_kind:     hidden_grid_dims
      - .offset:         240
        .size:           8
        .value_kind:     hidden_multigrid_sync_arg
      - .offset:         272
        .size:           4
        .value_kind:     hidden_dynamic_lds_size
    .group_segment_fixed_size: 0
    .kernarg_segment_align: 8
    .kernarg_segment_size: 408
    .language:       OpenCL C
    .language_version:
      - 2
      - 0
    .max_flat_workgroup_size: 512
    .name:           _Z9block_fwd4Args
    .private_segment_fixed_size: 0
    .sgpr_count:     108
    .sgpr_spill_count: 5
    .symbol:         _Z9block_fwd4Args.kd
    .uniform_work_group_size: 1
    .uses_dynamic_stack: false
    .vgpr_count:     240
    .vgpr_spill_count: 0
    .wavefront_size: 64
